# DF loop rotated: PV(T-1) V fragments pre-read across the barrier, MFMA order O0,P,Q,O1-3; SB flag reads as two b128
# speedup vs baseline: 1.0506x; 1.0072x over previous
; DI void df_scores(const LAS char* Kst, const DfCtx& c, f32x16& p, f32x16& q, int kv0) {
;     const float bb = c.c0 + c.sl * (float)kv0;
;     bf16x8 k0[4], k1[4];
; #pragma unroll
;     for (int d0 = 0; d0 < 4; ++d0) k0[d0] = ldsv(Kst + c.kad[d0]);
;     MEMFENCE();
; #pragma unroll
;     for (int r = 0; r < 16; ++r) p[r] = __builtin_fmaf(c.sl, (float)((r & 3) + 8 * (r >> 2)), bb);
;     PIN4(k0);
; #pragma unroll
;     for (int d0 = 0; d0 < 4; ++d0) p = MFMA32(k0[d0], c.qf[d0], p);
; #pragma unroll
;     for (int d0 = 0; d0 < 4; ++d0) k1[d0] = ldsv(Kst + c.kad[d0] + 8192);
;     MEMFENCE();
; template <bool PV> DI void df_pv_exp(const LAS char* Vst, const DfCtx& c, const bf16x8 (&pw)[4], f32x16 (&O)[4], f32x16& p, f32x16& q, bf16x8 (&pwN)[4], float& l, bool dg, int kv0) {
;     bf16x8 v0[4];
;     if (PV) {
; #pragma unroll
;         for (int ks = 0; ks < 4; ++ks) v0[ks] = ldsv(Vst + c.vad[ks]);
;         MEMFENCE(); }
; #pragma unroll
;     for (int r = 0; r < 16; ++r) p[r] = ex2(p[r]);
;     if (PV) {
;         PIN4(v0);
; #pragma unroll
;         for (int ks = 0; ks < 4; ++ks) O[0] = MFMA32(v0[ks], pw[ks], O[0]);
; #pragma unroll
;         for (int ks = 0; ks < 4; ++ks) v0[ks] = ldsv(Vst + c.vad[ks] + 4096);
;         MEMFENCE(); }
; #pragma unroll
;     for (int r = 0; r < 16; ++r) q[r] = ex2(q[r]);
;     if (PV) {
;         PIN4(v0);
; #pragma unroll
;         for (int ks = 0; ks < 4; ++ks) O[1] = MFMA32(v0[ks], pw[ks], O[1]);
; #pragma unroll
;         for (int ks = 0; ks < 4; ++ks) v0[ks] = ldsv(Vst + c.vad[ks] + 8192);
;         MEMFENCE(); }
;     if (dg) { const int lim = c.tq - kv0 - 4 * c.hi;
; #pragma unroll
;         for (int r = 0; r < 16; ++r) { if ((r & 3) + 8 * (r >> 2) > lim) p[r] = 0.f; if (32 + (r & 3) + 8 * (r >> 2) > lim) q[r] = 0.f; } }
;     float ls = 0.f;
; #pragma unroll
;     for (int r = 0; r < 16; ++r) ls += p[r] + q[r];
;     l += ls;
;     if (PV) {
;         PIN4(v0);
; #pragma unroll
;         for (int ks = 0; ks < 4; ++ks) O[2] = MFMA32(v0[ks], pw[ks], O[2]);
; #pragma unroll
;         for (int ks = 0; ks < 4; ++ks) v0[ks] = ldsv(Vst + c.vad[ks] + 12288);
;         MEMFENCE(); }
;     pwN[0] = pack8<0>(p); pwN[1] = pack8<1>(p); pwN[2] = pack8<0>(q); pwN[3] = pack8<1>(q);
;     if (PV) {
;         PIN4(v0);
; #pragma unroll
;         for (int ks = 0; ks < 4; ++ks) O[3] = MFMA32(v0[ks], pw[ks], O[3]);
;     }
; }
.LBB0_381:
	s_mov_b32 s60, s1
	v_lshl_add_u64 v[172:173], s[78:79], 0, v[168:169]
	v_lshl_add_u64 v[170:171], s[78:79], 0, v[166:167]
	v_add_u32_e32 v212, 0x10000, v248
	v_add_u32_e32 v213, 0x10000, v247
	v_add_u32_e32 v214, 0x10000, v246
	v_add_u32_e32 v215, 0x10000, v245
	v_mov_b32_e32 v216, 0
	v_mov_b32_e32 v219, v194
	ds_read_b128 v[66:69], v212 offset:0
	ds_read_b128 v[70:73], v213 offset:0
	ds_read_b128 v[74:77], v214 offset:0
	ds_read_b128 v[78:81], v215 offset:0
	s_waitcnt vmcnt(4)
	s_barrier
	ds_read_b128 v[98:101], v251 offset:16384
	ds_read_b128 v[102:105], v252 offset:16384
	ds_read_b128 v[106:109], v232 offset:16384
	ds_read_b128 v[110:113], v234 offset:16384
	ds_read_b128 v[180:183], v251 offset:24576
	ds_read_b128 v[184:187], v252 offset:24576
	ds_read_b128 v[188:191], v232 offset:24576
	ds_read_b128 v[192:195], v234 offset:24576
	s_add_i32 s1, s0, -192
	v_cvt_f32_u32_e32 v218, s1
	s_nop 0
	v_fma_f32 v0, v179, v218, v244
	s_waitcnt lgkmcnt(8)
	v_mfma_f32_32x32x16_bf16 v[50:65], v[66:69], v[158:161], v[50:65]
	v_fma_f32 v82, 0, v179, v0
	v_add_f32_e32 v83, v179, v0
	v_fma_f32 v84, v178, s8, v0
	v_fma_f32 v85, v179, s9, v0
	v_fma_f32 v86, v178, s28, v0
	v_fma_f32 v87, v179, s29, v0
	v_fma_f32 v88, v178, s30, v0
	v_fma_f32 v89, v179, s31, v0
	v_mfma_f32_32x32x16_bf16 v[50:65], v[70:73], v[154:157], v[50:65]
	v_fma_f32 v90, v178, s34, v0
	v_fma_f32 v91, v179, s35, v0
	v_fma_f32 v92, v178, s10, v0
	v_fma_f32 v93, v179, s11, v0
	v_fma_f32 v94, v178, s20, v0
	v_fma_f32 v95, v179, s21, v0
	v_fma_f32 v96, v178, s2, v0
	v_fma_f32 v97, v179, s3, v0
	v_mfma_f32_32x32x16_bf16 v[50:65], v[74:77], v[150:153], v[50:65]
	v_add_f32_e32 v217, v249, v0
	v_fma_f32 v114, 0, v179, v217
	v_add_f32_e32 v115, v179, v217
	v_fma_f32 v116, v178, s8, v217
	v_fma_f32 v117, v179, s9, v217
	v_fma_f32 v118, v178, s28, v217
	v_fma_f32 v119, v179, s29, v217
	v_fma_f32 v120, v178, s30, v217
	v_mfma_f32_32x32x16_bf16 v[50:65], v[78:81], v[146:149], v[50:65]
	v_fma_f32 v121, v179, s31, v217
	v_fma_f32 v122, v178, s34, v217
	v_fma_f32 v123, v179, s35, v217
	v_fma_f32 v124, v178, s10, v217
	v_fma_f32 v125, v179, s11, v217
	v_fma_f32 v126, v178, s20, v217
	v_fma_f32 v127, v179, s21, v217
	v_fma_f32 v128, v178, s2, v217
	ds_read_b128 v[66:69], v212 offset:4096
	ds_read_b128 v[70:73], v213 offset:4096
	ds_read_b128 v[74:77], v214 offset:4096
	ds_read_b128 v[78:81], v215 offset:4096
	s_waitcnt lgkmcnt(8)
	v_mfma_f32_32x32x16_bf16 v[82:97], v[98:101], v[130:133], v[82:97]
	v_fma_f32 v129, v179, s3, v217
	s_mov_b64 s[12:13], 0x7030000
	v_lshl_add_u64 v[220:221], v[172:173], 0, s[12:13]
	s_add_i32 s4, s5, 0xc000
	s_mov_b32 m0, s4
	s_nop 0
	global_load_lds_dwordx4 v[220:221], off
	v_mfma_f32_32x32x16_bf16 v[82:97], v[102:105], v[134:137], v[82:97]
	s_mov_b64 s[12:13], 0x7038000
	v_lshl_add_u64 v[222:223], v[172:173], 0, s[12:13]
	s_add_i32 s4, s5, 0xe000
	s_mov_b32 m0, s4
	s_nop 0
	global_load_lds_dwordx4 v[222:223], off
	v_mfma_f32_32x32x16_bf16 v[82:97], v[106:109], v[138:141], v[82:97]
	s_mov_b64 s[12:13], 0xa00c000
	v_lshl_add_u64 v[220:221], v[170:171], 0, s[12:13]
	s_add_i32 s4, s5, 0x1c000
	s_mov_b32 m0, s4
	s_nop 0
	global_load_lds_dwordx4 v[220:221], off
	v_mfma_f32_32x32x16_bf16 v[82:97], v[110:113], v[142:145], v[82:97]
	s_mov_b64 s[12:13], 0xa00e000
	v_lshl_add_u64 v[222:223], v[170:171], 0, s[12:13]
	s_add_i32 s4, s5, 0x1e000
	s_mov_b32 m0, s4
	s_nop 0
	global_load_lds_dwordx4 v[222:223], off
	ds_read_b128 v[98:101], v212 offset:8192
	ds_read_b128 v[102:105], v213 offset:8192
	ds_read_b128 v[106:109], v214 offset:8192
	ds_read_b128 v[110:113], v215 offset:8192
	s_waitcnt lgkmcnt(8)
	v_mfma_f32_32x32x16_bf16 v[114:129], v[180:183], v[130:133], v[114:129]
	v_exp_f32_e32 v82, v82
	v_exp_f32_e32 v83, v83
	v_exp_f32_e32 v84, v84
	v_mfma_f32_32x32x16_bf16 v[114:129], v[184:187], v[134:137], v[114:129]
	v_exp_f32_e32 v85, v85
	v_exp_f32_e32 v86, v86
	v_exp_f32_e32 v87, v87
	v_mfma_f32_32x32x16_bf16 v[114:129], v[188:191], v[138:141], v[114:129]
	v_exp_f32_e32 v88, v88
	v_exp_f32_e32 v89, v89
	v_exp_f32_e32 v90, v90
	v_mfma_f32_32x32x16_bf16 v[114:129], v[192:195], v[142:145], v[114:129]
	v_exp_f32_e32 v91, v91
	v_exp_f32_e32 v92, v92
	v_exp_f32_e32 v93, v93
	ds_read_b128 v[180:183], v212 offset:12288
	ds_read_b128 v[184:187], v213 offset:12288
	ds_read_b128 v[188:191], v214 offset:12288
	ds_read_b128 v[192:195], v215 offset:12288
	s_waitcnt lgkmcnt(8)
	v_mfma_f32_32x32x16_bf16 v[34:49], v[66:69], v[158:161], v[34:49]
	v_exp_f32_e32 v94, v94
	v_exp_f32_e32 v95, v95
	v_exp_f32_e32 v96, v96
	v_mfma_f32_32x32x16_bf16 v[34:49], v[70:73], v[154:157], v[34:49]
	v_exp_f32_e32 v97, v97
	v_add_f32_e32 v219, v219, v82
	v_add_f32_e32 v219, v219, v83
	v_cvt_pk_bf16_f32 v196, v82, v83
	v_add_f32_e32 v219, v219, v84
	v_mfma_f32_32x32x16_bf16 v[34:49], v[74:77], v[150:153], v[34:49]
	v_add_f32_e32 v219, v219, v85
	v_cvt_pk_bf16_f32 v197, v84, v85
	v_add_f32_e32 v219, v219, v86
	v_add_f32_e32 v219, v219, v87
	v_cvt_pk_bf16_f32 v198, v86, v87
	v_add_f32_e32 v219, v219, v88
	v_mfma_f32_32x32x16_bf16 v[34:49], v[78:81], v[146:149], v[34:49]
	v_add_f32_e32 v219, v219, v89
	v_cvt_pk_bf16_f32 v199, v88, v89
	v_exp_f32_e32 v114, v114
	v_exp_f32_e32 v115, v115
	ds_read_b128 v[66:69], v212 offset:16384
	ds_read_b128 v[70:73], v213 offset:16384
	ds_read_b128 v[74:77], v214 offset:16384
	ds_read_b128 v[78:81], v215 offset:16384
	s_waitcnt lgkmcnt(8)
; DI void df_scores(const LAS char* Kst, const DfCtx& c, f32x16& p, f32x16& q, int kv0) {
;     const float bb = c.c0 + c.sl * (float)kv0;
;     bf16x8 k0[4], k1[4];
; #pragma unroll
;     for (int d0 = 0; d0 < 4; ++d0) k0[d0] = ldsv(Kst + c.kad[d0]);
;     MEMFENCE();
; #pragma unroll
;     for (int r = 0; r < 16; ++r) p[r] = __builtin_fmaf(c.sl, (float)((r & 3) + 8 * (r >> 2)), bb);
;     PIN4(k0);
; #pragma unroll
;     for (int d0 = 0; d0 < 4; ++d0) p = MFMA32(k0[d0], c.qf[d0], p);
; #pragma unroll
;     for (int d0 = 0; d0 < 4; ++d0) k1[d0] = ldsv(Kst + c.kad[d0] + 8192);
;     MEMFENCE();
; template <bool PV> DI void df_pv_exp(const LAS char* Vst, const DfCtx& c, const bf16x8 (&pw)[4], f32x16 (&O)[4], f32x16& p, f32x16& q, bf16x8 (&pwN)[4], float& l, bool dg, int kv0) {
;     bf16x8 v0[4];
;     if (PV) {
; #pragma unroll
;         for (int ks = 0; ks < 4; ++ks) v0[ks] = ldsv(Vst + c.vad[ks]);
;         MEMFENCE(); }
; #pragma unroll
;     for (int r = 0; r < 16; ++r) p[r] = ex2(p[r]);
;     if (PV) {
;         PIN4(v0);
; #pragma unroll
;         for (int ks = 0; ks < 4; ++ks) O[0] = MFMA32(v0[ks], pw[ks], O[0]);
; #pragma unroll
;         for (int ks = 0; ks < 4; ++ks) v0[ks] = ldsv(Vst + c.vad[ks] + 4096);
;         MEMFENCE(); }
; #pragma unroll
;     for (int r = 0; r < 16; ++r) q[r] = ex2(q[r]);
;     if (PV) {
;         PIN4(v0);
; #pragma unroll
;         for (int ks = 0; ks < 4; ++ks) O[1] = MFMA32(v0[ks], pw[ks], O[1]);
; #pragma unroll
;         for (int ks = 0; ks < 4; ++ks) v0[ks] = ldsv(Vst + c.vad[ks] + 8192);
;         MEMFENCE(); }
;     if (dg) { const int lim = c.tq - kv0 - 4 * c.hi;
; #pragma unroll
;         for (int r = 0; r < 16; ++r) { if ((r & 3) + 8 * (r >> 2) > lim) p[r] = 0.f; if (32 + (r & 3) + 8 * (r >> 2) > lim) q[r] = 0.f; } }
;     float ls = 0.f;
; #pragma unroll
;     for (int r = 0; r < 16; ++r) ls += p[r] + q[r];
;     l += ls;
;     if (PV) {
;         PIN4(v0);
; #pragma unroll
;         for (int ks = 0; ks < 4; ++ks) O[2] = MFMA32(v0[ks], pw[ks], O[2]);
; #pragma unroll
;         for (int ks = 0; ks < 4; ++ks) v0[ks] = ldsv(Vst + c.vad[ks] + 12288);
;         MEMFENCE(); }
;     pwN[0] = pack8<0>(p); pwN[1] = pack8<1>(p); pwN[2] = pack8<0>(q); pwN[3] = pack8<1>(q);
;     if (PV) {
;         PIN4(v0);
; #pragma unroll
;         for (int ks = 0; ks < 4; ++ks) O[3] = MFMA32(v0[ks], pw[ks], O[3]);
;     }
; }
	v_mfma_f32_32x32x16_bf16 v[18:33], v[98:101], v[158:161], v[18:33]
	v_exp_f32_e32 v116, v116
	v_exp_f32_e32 v117, v117
	v_exp_f32_e32 v118, v118
	v_mfma_f32_32x32x16_bf16 v[18:33], v[102:105], v[154:157], v[18:33]
	v_exp_f32_e32 v119, v119
	v_exp_f32_e32 v120, v120
	v_exp_f32_e32 v121, v121
	v_mfma_f32_32x32x16_bf16 v[18:33], v[106:109], v[150:153], v[18:33]
	v_exp_f32_e32 v122, v122
	v_exp_f32_e32 v123, v123
	v_exp_f32_e32 v124, v124
	v_mfma_f32_32x32x16_bf16 v[18:33], v[110:113], v[146:149], v[18:33]
	v_exp_f32_e32 v125, v125
	v_exp_f32_e32 v126, v126
	v_exp_f32_e32 v127, v127
	s_waitcnt lgkmcnt(4)
	v_mfma_f32_32x32x16_bf16 v[2:17], v[180:183], v[158:161], v[2:17]
	v_exp_f32_e32 v128, v128
	v_exp_f32_e32 v129, v129
	v_add_f32_e32 v219, v219, v90
	v_add_f32_e32 v219, v219, v91
	v_mfma_f32_32x32x16_bf16 v[2:17], v[184:187], v[154:157], v[2:17]
	v_cvt_pk_bf16_f32 v200, v90, v91
	v_add_f32_e32 v219, v219, v92
	v_add_f32_e32 v219, v219, v93
	v_cvt_pk_bf16_f32 v201, v92, v93
	v_add_f32_e32 v219, v219, v94
	v_add_f32_e32 v219, v219, v95
	v_mfma_f32_32x32x16_bf16 v[2:17], v[188:191], v[150:153], v[2:17]
	v_cvt_pk_bf16_f32 v202, v94, v95
	v_add_f32_e32 v219, v219, v96
	v_add_f32_e32 v219, v219, v97
	v_cvt_pk_bf16_f32 v203, v96, v97
	v_add_f32_e32 v216, v216, v114
	v_add_f32_e32 v216, v216, v115
	v_mfma_f32_32x32x16_bf16 v[2:17], v[192:195], v[146:149], v[2:17]
	v_cvt_pk_bf16_f32 v204, v114, v115
	v_add_f32_e32 v216, v216, v116
	v_add_f32_e32 v216, v216, v117
	v_cvt_pk_bf16_f32 v205, v116, v117
	v_add_f32_e32 v216, v216, v118
	v_add_f32_e32 v216, v216, v119
	v_cvt_pk_bf16_f32 v206, v118, v119
	v_add_f32_e32 v216, v216, v120
	v_add_f32_e32 v216, v216, v121
	v_cvt_pk_bf16_f32 v207, v120, v121
	v_add_f32_e32 v216, v216, v122
	v_add_f32_e32 v216, v216, v123
	v_cvt_pk_bf16_f32 v208, v122, v123
	v_add_f32_e32 v216, v216, v124
	v_add_f32_e32 v216, v216, v125
	v_cvt_pk_bf16_f32 v209, v124, v125
	v_add_f32_e32 v216, v216, v126
	v_add_f32_e32 v216, v216, v127
	v_cvt_pk_bf16_f32 v210, v126, v127
	v_add_f32_e32 v216, v216, v128
	v_add_f32_e32 v216, v216, v129
	v_cvt_pk_bf16_f32 v211, v128, v129
	s_waitcnt vmcnt(4)
	s_barrier
	ds_read_b128 v[98:101], v251 offset:32768
	ds_read_b128 v[102:105], v252 offset:32768
	ds_read_b128 v[106:109], v232 offset:32768
	ds_read_b128 v[110:113], v234 offset:32768
	ds_read_b128 v[180:183], v251 offset:40960
	ds_read_b128 v[184:187], v252 offset:40960
	ds_read_b128 v[188:191], v232 offset:40960
	ds_read_b128 v[192:195], v234 offset:40960
	s_add_i32 s1, s0, -128
	v_cvt_f32_u32_e32 v218, s1
	s_nop 0
	v_fma_f32 v0, v179, v218, v244
	s_waitcnt lgkmcnt(8)
	v_mfma_f32_32x32x16_bf16 v[50:65], v[66:69], v[196:199], v[50:65]
	v_fma_f32 v82, 0, v179, v0
	v_add_f32_e32 v83, v179, v0
	v_fma_f32 v84, v178, s8, v0
	v_fma_f32 v85, v179, s9, v0
	v_fma_f32 v86, v178, s28, v0
	v_fma_f32 v87, v179, s29, v0
	v_fma_f32 v88, v178, s30, v0
	v_fma_f32 v89, v179, s31, v0
	v_mfma_f32_32x32x16_bf16 v[50:65], v[70:73], v[200:203], v[50:65]
	v_fma_f32 v90, v178, s34, v0
	v_fma_f32 v91, v179, s35, v0
	v_fma_f32 v92, v178, s10, v0
	v_fma_f32 v93, v179, s11, v0
	v_fma_f32 v94, v178, s20, v0
	v_fma_f32 v95, v179, s21, v0
	v_fma_f32 v96, v178, s2, v0
	v_fma_f32 v97, v179, s3, v0
	v_mfma_f32_32x32x16_bf16 v[50:65], v[74:77], v[204:207], v[50:65]
	v_add_f32_e32 v217, v249, v0
	v_fma_f32 v114, 0, v179, v217
	v_add_f32_e32 v115, v179, v217
	v_fma_f32 v116, v178, s8, v217
	v_fma_f32 v117, v179, s9, v217
	v_fma_f32 v118, v178, s28, v217
	v_fma_f32 v119, v179, s29, v217
	v_fma_f32 v120, v178, s30, v217
	v_mfma_f32_32x32x16_bf16 v[50:65], v[78:81], v[208:211], v[50:65]
	v_fma_f32 v121, v179, s31, v217
	v_fma_f32 v122, v178, s34, v217
	v_fma_f32 v123, v179, s35, v217
	v_fma_f32 v124, v178, s10, v217
	v_fma_f32 v125, v179, s11, v217
	v_fma_f32 v126, v178, s20, v217
	v_fma_f32 v127, v179, s21, v217
	v_fma_f32 v128, v178, s2, v217
	ds_read_b128 v[66:69], v212 offset:20480
	ds_read_b128 v[70:73], v213 offset:20480
	ds_read_b128 v[74:77], v214 offset:20480
	ds_read_b128 v[78:81], v215 offset:20480
	s_waitcnt lgkmcnt(8)
	v_mfma_f32_32x32x16_bf16 v[82:97], v[98:101], v[130:133], v[82:97]
	v_fma_f32 v129, v179, s3, v217
	s_mov_b64 s[12:13], 0x7040000
	v_lshl_add_u64 v[220:221], v[172:173], 0, s[12:13]
	s_mov_b32 m0, s5
	s_nop 0
	global_load_lds_dwordx4 v[220:221], off
	v_mfma_f32_32x32x16_bf16 v[82:97], v[102:105], v[134:137], v[82:97]
	s_mov_b64 s[12:13], 0x7048000
	v_lshl_add_u64 v[222:223], v[172:173], 0, s[12:13]
	s_add_i32 s4, s5, 0x2000
	s_mov_b32 m0, s4
	s_nop 0
	global_load_lds_dwordx4 v[222:223], off
	v_mfma_f32_32x32x16_bf16 v[82:97], v[106:109], v[138:141], v[82:97]
	s_mov_b64 s[12:13], 0xa010000
	v_lshl_add_u64 v[220:221], v[170:171], 0, s[12:13]
	s_add_i32 s4, s5, 0x10000
	s_mov_b32 m0, s4
	s_nop 0
	global_load_lds_dwordx4 v[220:221], off
	v_mfma_f32_32x32x16_bf16 v[82:97], v[110:113], v[142:145], v[82:97]
	s_mov_b64 s[12:13], 0xa012000
	v_lshl_add_u64 v[222:223], v[170:171], 0, s[12:13]
	s_add_i32 s4, s5, 0x12000
	s_mov_b32 m0, s4
	s_nop 0
	global_load_lds_dwordx4 v[222:223], off
	ds_read_b128 v[98:101], v212 offset:24576
	ds_read_b128 v[102:105], v213 offset:24576
	ds_read_b128 v[106:109], v214 offset:24576
	ds_read_b128 v[110:113], v215 offset:24576
	s_waitcnt lgkmcnt(8)
	v_mfma_f32_32x32x16_bf16 v[114:129], v[180:183], v[130:133], v[114:129]
	v_exp_f32_e32 v82, v82
	v_exp_f32_e32 v83, v83
	v_exp_f32_e32 v84, v84
	v_mfma_f32_32x32x16_bf16 v[114:129], v[184:187], v[134:137], v[114:129]
	v_exp_f32_e32 v85, v85
	v_exp_f32_e32 v86, v86
	v_exp_f32_e32 v87, v87
	v_mfma_f32_32x32x16_bf16 v[114:129], v[188:191], v[138:141], v[114:129]
	v_exp_f32_e32 v88, v88
	v_exp_f32_e32 v89, v89
	v_exp_f32_e32 v90, v90
	v_mfma_f32_32x32x16_bf16 v[114:129], v[192:195], v[142:145], v[114:129]
	v_exp_f32_e32 v91, v91
	v_exp_f32_e32 v92, v92
	v_exp_f32_e32 v93, v93
	ds_read_b128 v[180:183], v212 offset:28672
	ds_read_b128 v[184:187], v213 offset:28672
	ds_read_b128 v[188:191], v214 offset:28672
	ds_read_b128 v[192:195], v215 offset:28672
	s_waitcnt lgkmcnt(8)
; DI void df_scores(const LAS char* Kst, const DfCtx& c, f32x16& p, f32x16& q, int kv0) {
;     const float bb = c.c0 + c.sl * (float)kv0;
;     bf16x8 k0[4], k1[4];
; #pragma unroll
;     for (int d0 = 0; d0 < 4; ++d0) k0[d0] = ldsv(Kst + c.kad[d0]);
;     MEMFENCE();
; #pragma unroll
;     for (int r = 0; r < 16; ++r) p[r] = __builtin_fmaf(c.sl, (float)((r & 3) + 8 * (r >> 2)), bb);
;     PIN4(k0);
; #pragma unroll
;     for (int d0 = 0; d0 < 4; ++d0) p = MFMA32(k0[d0], c.qf[d0], p);
; #pragma unroll
;     for (int d0 = 0; d0 < 4; ++d0) k1[d0] = ldsv(Kst + c.kad[d0] + 8192);
;     MEMFENCE();
; template <bool PV> DI void df_pv_exp(const LAS char* Vst, const DfCtx& c, const bf16x8 (&pw)[4], f32x16 (&O)[4], f32x16& p, f32x16& q, bf16x8 (&pwN)[4], float& l, bool dg, int kv0) {
;     bf16x8 v0[4];
;     if (PV) {
; #pragma unroll
;         for (int ks = 0; ks < 4; ++ks) v0[ks] = ldsv(Vst + c.vad[ks]);
;         MEMFENCE(); }
; #pragma unroll
;     for (int r = 0; r < 16; ++r) p[r] = ex2(p[r]);
;     if (PV) {
;         PIN4(v0);
; #pragma unroll
;         for (int ks = 0; ks < 4; ++ks) O[0] = MFMA32(v0[ks], pw[ks], O[0]);
; #pragma unroll
;         for (int ks = 0; ks < 4; ++ks) v0[ks] = ldsv(Vst + c.vad[ks] + 4096);
;         MEMFENCE(); }
; #pragma unroll
;     for (int r = 0; r < 16; ++r) q[r] = ex2(q[r]);
;     if (PV) {
;         PIN4(v0);
; #pragma unroll
;         for (int ks = 0; ks < 4; ++ks) O[1] = MFMA32(v0[ks], pw[ks], O[1]);
; #pragma unroll
;         for (int ks = 0; ks < 4; ++ks) v0[ks] = ldsv(Vst + c.vad[ks] + 8192);
;         MEMFENCE(); }
;     if (dg) { const int lim = c.tq - kv0 - 4 * c.hi;
; #pragma unroll
;         for (int r = 0; r < 16; ++r) { if ((r & 3) + 8 * (r >> 2) > lim) p[r] = 0.f; if (32 + (r & 3) + 8 * (r >> 2) > lim) q[r] = 0.f; } }
;     float ls = 0.f;
; #pragma unroll
;     for (int r = 0; r < 16; ++r) ls += p[r] + q[r];
;     l += ls;
;     if (PV) {
;         PIN4(v0);
; #pragma unroll
;         for (int ks = 0; ks < 4; ++ks) O[2] = MFMA32(v0[ks], pw[ks], O[2]);
; #pragma unroll
;         for (int ks = 0; ks < 4; ++ks) v0[ks] = ldsv(Vst + c.vad[ks] + 12288);
;         MEMFENCE(); }
;     pwN[0] = pack8<0>(p); pwN[1] = pack8<1>(p); pwN[2] = pack8<0>(q); pwN[3] = pack8<1>(q);
;     if (PV) {
;         PIN4(v0);
; #pragma unroll
;         for (int ks = 0; ks < 4; ++ks) O[3] = MFMA32(v0[ks], pw[ks], O[3]);
;     }
; }
	v_mfma_f32_32x32x16_bf16 v[34:49], v[66:69], v[196:199], v[34:49]
	v_exp_f32_e32 v94, v94
	v_exp_f32_e32 v95, v95
	v_exp_f32_e32 v96, v96
	v_mfma_f32_32x32x16_bf16 v[34:49], v[70:73], v[200:203], v[34:49]
	v_exp_f32_e32 v97, v97
	v_add_f32_e32 v219, v219, v82
	v_add_f32_e32 v219, v219, v83
	v_cvt_pk_bf16_f32 v158, v82, v83
	v_add_f32_e32 v219, v219, v84
	v_mfma_f32_32x32x16_bf16 v[34:49], v[74:77], v[204:207], v[34:49]
	v_add_f32_e32 v219, v219, v85
	v_cvt_pk_bf16_f32 v159, v84, v85
	v_add_f32_e32 v219, v219, v86
	v_add_f32_e32 v219, v219, v87
	v_cvt_pk_bf16_f32 v160, v86, v87
	v_add_f32_e32 v219, v219, v88
	v_mfma_f32_32x32x16_bf16 v[34:49], v[78:81], v[208:211], v[34:49]
	v_add_f32_e32 v219, v219, v89
	v_cvt_pk_bf16_f32 v161, v88, v89
	v_exp_f32_e32 v114, v114
	v_exp_f32_e32 v115, v115
	ds_read_b128 v[66:69], v212 offset:32768
	ds_read_b128 v[70:73], v213 offset:32768
	ds_read_b128 v[74:77], v214 offset:32768
	ds_read_b128 v[78:81], v215 offset:32768
	s_waitcnt lgkmcnt(8)
	v_mfma_f32_32x32x16_bf16 v[18:33], v[98:101], v[196:199], v[18:33]
	v_exp_f32_e32 v116, v116
	v_exp_f32_e32 v117, v117
	v_exp_f32_e32 v118, v118
	v_mfma_f32_32x32x16_bf16 v[18:33], v[102:105], v[200:203], v[18:33]
	v_exp_f32_e32 v119, v119
	v_exp_f32_e32 v120, v120
	v_exp_f32_e32 v121, v121
	v_mfma_f32_32x32x16_bf16 v[18:33], v[106:109], v[204:207], v[18:33]
	v_exp_f32_e32 v122, v122
	v_exp_f32_e32 v123, v123
	v_exp_f32_e32 v124, v124
	v_mfma_f32_32x32x16_bf16 v[18:33], v[110:113], v[208:211], v[18:33]
	v_exp_f32_e32 v125, v125
	v_exp_f32_e32 v126, v126
	v_exp_f32_e32 v127, v127
	s_waitcnt lgkmcnt(4)
	v_mfma_f32_32x32x16_bf16 v[2:17], v[180:183], v[196:199], v[2:17]
	v_exp_f32_e32 v128, v128
	v_exp_f32_e32 v129, v129
	v_add_f32_e32 v219, v219, v90
	v_add_f32_e32 v219, v219, v91
	v_mfma_f32_32x32x16_bf16 v[2:17], v[184:187], v[200:203], v[2:17]
	v_cvt_pk_bf16_f32 v154, v90, v91
	v_add_f32_e32 v219, v219, v92
	v_add_f32_e32 v219, v219, v93
	v_cvt_pk_bf16_f32 v155, v92, v93
	v_add_f32_e32 v219, v219, v94
	v_add_f32_e32 v219, v219, v95
	v_mfma_f32_32x32x16_bf16 v[2:17], v[188:191], v[204:207], v[2:17]
	v_cvt_pk_bf16_f32 v156, v94, v95
	v_add_f32_e32 v219, v219, v96
	v_add_f32_e32 v219, v219, v97
	v_cvt_pk_bf16_f32 v157, v96, v97
	v_add_f32_e32 v216, v216, v114
	v_add_f32_e32 v216, v216, v115
	v_mfma_f32_32x32x16_bf16 v[2:17], v[192:195], v[208:211], v[2:17]
	v_cvt_pk_bf16_f32 v150, v114, v115
	v_add_f32_e32 v216, v216, v116
	v_add_f32_e32 v216, v216, v117
	v_cvt_pk_bf16_f32 v151, v116, v117
	v_add_f32_e32 v216, v216, v118
	v_add_f32_e32 v216, v216, v119
	v_cvt_pk_bf16_f32 v152, v118, v119
	v_add_f32_e32 v216, v216, v120
	v_add_f32_e32 v216, v216, v121
	v_cvt_pk_bf16_f32 v153, v120, v121
	v_add_f32_e32 v216, v216, v122
	v_add_f32_e32 v216, v216, v123
	v_cvt_pk_bf16_f32 v146, v122, v123
	v_add_f32_e32 v216, v216, v124
	v_add_f32_e32 v216, v216, v125
	v_cvt_pk_bf16_f32 v147, v124, v125
	v_add_f32_e32 v216, v216, v126
	v_add_f32_e32 v216, v216, v127
	v_cvt_pk_bf16_f32 v148, v126, v127
	v_add_f32_e32 v216, v216, v128
	v_add_f32_e32 v216, v216, v129
	v_cvt_pk_bf16_f32 v149, v128, v129
	s_waitcnt vmcnt(4)
	s_barrier
	ds_read_b128 v[98:101], v251 offset:49152
	ds_read_b128 v[102:105], v252 offset:49152
	ds_read_b128 v[106:109], v232 offset:49152
	ds_read_b128 v[110:113], v234 offset:49152
	ds_read_b128 v[180:183], v251 offset:57344
	ds_read_b128 v[184:187], v252 offset:57344
	ds_read_b128 v[188:191], v232 offset:57344
	ds_read_b128 v[192:195], v234 offset:57344
	s_add_i32 s1, s0, -64
	v_cvt_f32_u32_e32 v218, s1
	s_nop 0
	v_fma_f32 v0, v179, v218, v244
	s_waitcnt lgkmcnt(8)
	v_mfma_f32_32x32x16_bf16 v[50:65], v[66:69], v[158:161], v[50:65]
	v_fma_f32 v82, 0, v179, v0
	v_add_f32_e32 v83, v179, v0
	v_fma_f32 v84, v178, s8, v0
	v_fma_f32 v85, v179, s9, v0
	v_fma_f32 v86, v178, s28, v0
	v_fma_f32 v87, v179, s29, v0
	v_fma_f32 v88, v178, s30, v0
	v_fma_f32 v89, v179, s31, v0
	v_mfma_f32_32x32x16_bf16 v[50:65], v[70:73], v[154:157], v[50:65]
	v_fma_f32 v90, v178, s34, v0
	v_fma_f32 v91, v179, s35, v0
	v_fma_f32 v92, v178, s10, v0
	v_fma_f32 v93, v179, s11, v0
	v_fma_f32 v94, v178, s20, v0
	v_fma_f32 v95, v179, s21, v0
	v_fma_f32 v96, v178, s2, v0
	v_fma_f32 v97, v179, s3, v0
	v_mfma_f32_32x32x16_bf16 v[50:65], v[74:77], v[150:153], v[50:65]
	v_add_f32_e32 v217, v249, v0
	v_fma_f32 v114, 0, v179, v217
	v_add_f32_e32 v115, v179, v217
	v_fma_f32 v116, v178, s8, v217
	v_fma_f32 v117, v179, s9, v217
	v_fma_f32 v118, v178, s28, v217
	v_fma_f32 v119, v179, s29, v217
	v_fma_f32 v120, v178, s30, v217
	v_mfma_f32_32x32x16_bf16 v[50:65], v[78:81], v[146:149], v[50:65]
	v_fma_f32 v121, v179, s31, v217
	v_fma_f32 v122, v178, s34, v217
	v_fma_f32 v123, v179, s35, v217
	v_fma_f32 v124, v178, s10, v217
	v_fma_f32 v125, v179, s11, v217
	v_fma_f32 v126, v178, s20, v217
	v_fma_f32 v127, v179, s21, v217
	v_fma_f32 v128, v178, s2, v217
	ds_read_b128 v[66:69], v212 offset:36864
	ds_read_b128 v[70:73], v213 offset:36864
	ds_read_b128 v[74:77], v214 offset:36864
	ds_read_b128 v[78:81], v215 offset:36864
	s_waitcnt lgkmcnt(8)
; DI void df_scores(const LAS char* Kst, const DfCtx& c, f32x16& p, f32x16& q, int kv0) {
;     const float bb = c.c0 + c.sl * (float)kv0;
;     bf16x8 k0[4], k1[4];
; #pragma unroll
;     for (int d0 = 0; d0 < 4; ++d0) k0[d0] = ldsv(Kst + c.kad[d0]);
;     MEMFENCE();
; #pragma unroll
;     for (int r = 0; r < 16; ++r) p[r] = __builtin_fmaf(c.sl, (float)((r & 3) + 8 * (r >> 2)), bb);
;     PIN4(k0);
; #pragma unroll
;     for (int d0 = 0; d0 < 4; ++d0) p = MFMA32(k0[d0], c.qf[d0], p);
; #pragma unroll
;     for (int d0 = 0; d0 < 4; ++d0) k1[d0] = ldsv(Kst + c.kad[d0] + 8192);
;     MEMFENCE();
; template <bool PV> DI void df_pv_exp(const LAS char* Vst, const DfCtx& c, const bf16x8 (&pw)[4], f32x16 (&O)[4], f32x16& p, f32x16& q, bf16x8 (&pwN)[4], float& l, bool dg, int kv0) {
;     bf16x8 v0[4];
;     if (PV) {
; #pragma unroll
;         for (int ks = 0; ks < 4; ++ks) v0[ks] = ldsv(Vst + c.vad[ks]);
;         MEMFENCE(); }
; #pragma unroll
;     for (int r = 0; r < 16; ++r) p[r] = ex2(p[r]);
;     if (PV) {
;         PIN4(v0);
; #pragma unroll
;         for (int ks = 0; ks < 4; ++ks) O[0] = MFMA32(v0[ks], pw[ks], O[0]);
; #pragma unroll
;         for (int ks = 0; ks < 4; ++ks) v0[ks] = ldsv(Vst + c.vad[ks] + 4096);
;         MEMFENCE(); }
; #pragma unroll
;     for (int r = 0; r < 16; ++r) q[r] = ex2(q[r]);
;     if (PV) {
;         PIN4(v0);
; #pragma unroll
;         for (int ks = 0; ks < 4; ++ks) O[1] = MFMA32(v0[ks], pw[ks], O[1]);
; #pragma unroll
;         for (int ks = 0; ks < 4; ++ks) v0[ks] = ldsv(Vst + c.vad[ks] + 8192);
;         MEMFENCE(); }
;     if (dg) { const int lim = c.tq - kv0 - 4 * c.hi;
; #pragma unroll
;         for (int r = 0; r < 16; ++r) { if ((r & 3) + 8 * (r >> 2) > lim) p[r] = 0.f; if (32 + (r & 3) + 8 * (r >> 2) > lim) q[r] = 0.f; } }
;     float ls = 0.f;
; #pragma unroll
;     for (int r = 0; r < 16; ++r) ls += p[r] + q[r];
;     l += ls;
;     if (PV) {
;         PIN4(v0);
; #pragma unroll
;         for (int ks = 0; ks < 4; ++ks) O[2] = MFMA32(v0[ks], pw[ks], O[2]);
; #pragma unroll
;         for (int ks = 0; ks < 4; ++ks) v0[ks] = ldsv(Vst + c.vad[ks] + 12288);
;         MEMFENCE(); }
;     pwN[0] = pack8<0>(p); pwN[1] = pack8<1>(p); pwN[2] = pack8<0>(q); pwN[3] = pack8<1>(q);
;     if (PV) {
;         PIN4(v0);
; #pragma unroll
;         for (int ks = 0; ks < 4; ++ks) O[3] = MFMA32(v0[ks], pw[ks], O[3]);
;     }
; }
	v_mfma_f32_32x32x16_bf16 v[82:97], v[98:101], v[130:133], v[82:97]
	v_fma_f32 v129, v179, s3, v217
	s_mov_b64 s[12:13], 0x7050000
	v_lshl_add_u64 v[220:221], v[172:173], 0, s[12:13]
	s_add_i32 s4, s5, 0x4000
	s_mov_b32 m0, s4
	s_nop 0
	global_load_lds_dwordx4 v[220:221], off
	v_mfma_f32_32x32x16_bf16 v[82:97], v[102:105], v[134:137], v[82:97]
	s_mov_b64 s[12:13], 0x7058000
	v_lshl_add_u64 v[222:223], v[172:173], 0, s[12:13]
	s_add_i32 s4, s5, 0x6000
	s_mov_b32 m0, s4
	s_nop 0
	global_load_lds_dwordx4 v[222:223], off
	v_mfma_f32_32x32x16_bf16 v[82:97], v[106:109], v[138:141], v[82:97]
	s_mov_b64 s[12:13], 0xa014000
	v_lshl_add_u64 v[220:221], v[170:171], 0, s[12:13]
	s_add_i32 s4, s5, 0x14000
	s_mov_b32 m0, s4
	s_nop 0
	global_load_lds_dwordx4 v[220:221], off
	v_mfma_f32_32x32x16_bf16 v[82:97], v[110:113], v[142:145], v[82:97]
	s_mov_b64 s[12:13], 0xa016000
	v_lshl_add_u64 v[222:223], v[170:171], 0, s[12:13]
	s_add_i32 s4, s5, 0x16000
	s_mov_b32 m0, s4
	s_nop 0
	global_load_lds_dwordx4 v[222:223], off
	ds_read_b128 v[98:101], v212 offset:40960
	ds_read_b128 v[102:105], v213 offset:40960
	ds_read_b128 v[106:109], v214 offset:40960
	ds_read_b128 v[110:113], v215 offset:40960
	s_waitcnt lgkmcnt(8)
	v_mfma_f32_32x32x16_bf16 v[114:129], v[180:183], v[130:133], v[114:129]
	v_exp_f32_e32 v82, v82
	v_exp_f32_e32 v83, v83
	v_exp_f32_e32 v84, v84
	v_mfma_f32_32x32x16_bf16 v[114:129], v[184:187], v[134:137], v[114:129]
	v_exp_f32_e32 v85, v85
	v_exp_f32_e32 v86, v86
	v_exp_f32_e32 v87, v87
	v_mfma_f32_32x32x16_bf16 v[114:129], v[188:191], v[138:141], v[114:129]
	v_exp_f32_e32 v88, v88
	v_exp_f32_e32 v89, v89
	v_exp_f32_e32 v90, v90
	v_mfma_f32_32x32x16_bf16 v[114:129], v[192:195], v[142:145], v[114:129]
	v_exp_f32_e32 v91, v91
	v_exp_f32_e32 v92, v92
	v_exp_f32_e32 v93, v93
	ds_read_b128 v[180:183], v212 offset:45056
	ds_read_b128 v[184:187], v213 offset:45056
	ds_read_b128 v[188:191], v214 offset:45056
	ds_read_b128 v[192:195], v215 offset:45056
	s_waitcnt lgkmcnt(8)
	v_mfma_f32_32x32x16_bf16 v[34:49], v[66:69], v[158:161], v[34:49]
	v_exp_f32_e32 v94, v94
	v_exp_f32_e32 v95, v95
	v_exp_f32_e32 v96, v96
	v_mfma_f32_32x32x16_bf16 v[34:49], v[70:73], v[154:157], v[34:49]
	v_exp_f32_e32 v97, v97
	v_add_f32_e32 v219, v219, v82
	v_add_f32_e32 v219, v219, v83
	v_cvt_pk_bf16_f32 v196, v82, v83
	v_add_f32_e32 v219, v219, v84
	v_mfma_f32_32x32x16_bf16 v[34:49], v[74:77], v[150:153], v[34:49]
	v_add_f32_e32 v219, v219, v85
	v_cvt_pk_bf16_f32 v197, v84, v85
	v_add_f32_e32 v219, v219, v86
	v_add_f32_e32 v219, v219, v87
	v_cvt_pk_bf16_f32 v198, v86, v87
	v_add_f32_e32 v219, v219, v88
	v_mfma_f32_32x32x16_bf16 v[34:49], v[78:81], v[146:149], v[34:49]
	v_add_f32_e32 v219, v219, v89
	v_cvt_pk_bf16_f32 v199, v88, v89
	v_exp_f32_e32 v114, v114
	v_exp_f32_e32 v115, v115
	ds_read_b128 v[66:69], v212 offset:49152
	ds_read_b128 v[70:73], v213 offset:49152
	ds_read_b128 v[74:77], v214 offset:49152
	ds_read_b128 v[78:81], v215 offset:49152
	s_waitcnt lgkmcnt(8)
	v_mfma_f32_32x32x16_bf16 v[18:33], v[98:101], v[158:161], v[18:33]
	v_exp_f32_e32 v116, v116
	v_exp_f32_e32 v117, v117
	v_exp_f32_e32 v118, v118
	v_mfma_f32_32x32x16_bf16 v[18:33], v[102:105], v[154:157], v[18:33]
	v_exp_f32_e32 v119, v119
	v_exp_f32_e32 v120, v120
	v_exp_f32_e32 v121, v121
	v_mfma_f32_32x32x16_bf16 v[18:33], v[106:109], v[150:153], v[18:33]
	v_exp_f32_e32 v122, v122
	v_exp_f32_e32 v123, v123
	v_exp_f32_e32 v124, v124
	v_mfma_f32_32x32x16_bf16 v[18:33], v[110:113], v[146:149], v[18:33]
	v_exp_f32_e32 v125, v125
	v_exp_f32_e32 v126, v126
	v_exp_f32_e32 v127, v127
	s_waitcnt lgkmcnt(4)
	v_mfma_f32_32x32x16_bf16 v[2:17], v[180:183], v[158:161], v[2:17]
	v_exp_f32_e32 v128, v128
	v_exp_f32_e32 v129, v129
	v_add_f32_e32 v219, v219, v90
	v_add_f32_e32 v219, v219, v91
	v_mfma_f32_32x32x16_bf16 v[2:17], v[184:187], v[154:157], v[2:17]
	v_cvt_pk_bf16_f32 v200, v90, v91
	v_add_f32_e32 v219, v219, v92
	v_add_f32_e32 v219, v219, v93
	v_cvt_pk_bf16_f32 v201, v92, v93
	v_add_f32_e32 v219, v219, v94
	v_add_f32_e32 v219, v219, v95
	v_mfma_f32_32x32x16_bf16 v[2:17], v[188:191], v[150:153], v[2:17]
	v_cvt_pk_bf16_f32 v202, v94, v95
	v_add_f32_e32 v219, v219, v96
	v_add_f32_e32 v219, v219, v97
	v_cvt_pk_bf16_f32 v203, v96, v97
	v_add_f32_e32 v216, v216, v114
	v_add_f32_e32 v216, v216, v115
	v_mfma_f32_32x32x16_bf16 v[2:17], v[192:195], v[146:149], v[2:17]
	v_cvt_pk_bf16_f32 v204, v114, v115
	v_add_f32_e32 v216, v216, v116
	v_add_f32_e32 v216, v216, v117
	v_cvt_pk_bf16_f32 v205, v116, v117
	v_add_f32_e32 v216, v216, v118
	v_add_f32_e32 v216, v216, v119
	v_cvt_pk_bf16_f32 v206, v118, v119
	v_add_f32_e32 v216, v216, v120
	v_add_f32_e32 v216, v216, v121
	v_cvt_pk_bf16_f32 v207, v120, v121
	v_add_f32_e32 v216, v216, v122
	v_add_f32_e32 v216, v216, v123
	v_cvt_pk_bf16_f32 v208, v122, v123
	v_add_f32_e32 v216, v216, v124
	v_add_f32_e32 v216, v216, v125
	v_cvt_pk_bf16_f32 v209, v124, v125
	v_add_f32_e32 v216, v216, v126
	v_add_f32_e32 v216, v216, v127
	v_cvt_pk_bf16_f32 v210, v126, v127
	v_add_f32_e32 v216, v216, v128
	v_add_f32_e32 v216, v216, v129
	v_cvt_pk_bf16_f32 v211, v128, v129
	s_waitcnt vmcnt(4)
	s_barrier
; DI void df_scores(const LAS char* Kst, const DfCtx& c, f32x16& p, f32x16& q, int kv0) {
;     const float bb = c.c0 + c.sl * (float)kv0;
;     bf16x8 k0[4], k1[4];
; #pragma unroll
;     for (int d0 = 0; d0 < 4; ++d0) k0[d0] = ldsv(Kst + c.kad[d0]);
;     MEMFENCE();
; #pragma unroll
;     for (int r = 0; r < 16; ++r) p[r] = __builtin_fmaf(c.sl, (float)((r & 3) + 8 * (r >> 2)), bb);
;     PIN4(k0);
; #pragma unroll
;     for (int d0 = 0; d0 < 4; ++d0) p = MFMA32(k0[d0], c.qf[d0], p);
; #pragma unroll
;     for (int d0 = 0; d0 < 4; ++d0) k1[d0] = ldsv(Kst + c.kad[d0] + 8192);
;     MEMFENCE();
; template <bool PV> DI void df_pv_exp(const LAS char* Vst, const DfCtx& c, const bf16x8 (&pw)[4], f32x16 (&O)[4], f32x16& p, f32x16& q, bf16x8 (&pwN)[4], float& l, bool dg, int kv0) {
;     bf16x8 v0[4];
;     if (PV) {
; #pragma unroll
;         for (int ks = 0; ks < 4; ++ks) v0[ks] = ldsv(Vst + c.vad[ks]);
;         MEMFENCE(); }
; #pragma unroll
;     for (int r = 0; r < 16; ++r) p[r] = ex2(p[r]);
;     if (PV) {
;         PIN4(v0);
; #pragma unroll
;         for (int ks = 0; ks < 4; ++ks) O[0] = MFMA32(v0[ks], pw[ks], O[0]);
; #pragma unroll
;         for (int ks = 0; ks < 4; ++ks) v0[ks] = ldsv(Vst + c.vad[ks] + 4096);
;         MEMFENCE(); }
; #pragma unroll
;     for (int r = 0; r < 16; ++r) q[r] = ex2(q[r]);
;     if (PV) {
;         PIN4(v0);
; #pragma unroll
;         for (int ks = 0; ks < 4; ++ks) O[1] = MFMA32(v0[ks], pw[ks], O[1]);
; #pragma unroll
;         for (int ks = 0; ks < 4; ++ks) v0[ks] = ldsv(Vst + c.vad[ks] + 8192);
;         MEMFENCE(); }
;     if (dg) { const int lim = c.tq - kv0 - 4 * c.hi;
; #pragma unroll
;         for (int r = 0; r < 16; ++r) { if ((r & 3) + 8 * (r >> 2) > lim) p[r] = 0.f; if (32 + (r & 3) + 8 * (r >> 2) > lim) q[r] = 0.f; } }
;     float ls = 0.f;
; #pragma unroll
;     for (int r = 0; r < 16; ++r) ls += p[r] + q[r];
;     l += ls;
;     if (PV) {
;         PIN4(v0);
; #pragma unroll
;         for (int ks = 0; ks < 4; ++ks) O[2] = MFMA32(v0[ks], pw[ks], O[2]);
; #pragma unroll
;         for (int ks = 0; ks < 4; ++ks) v0[ks] = ldsv(Vst + c.vad[ks] + 12288);
;         MEMFENCE(); }
;     pwN[0] = pack8<0>(p); pwN[1] = pack8<1>(p); pwN[2] = pack8<0>(q); pwN[3] = pack8<1>(q);
;     if (PV) {
;         PIN4(v0);
; #pragma unroll
;         for (int ks = 0; ks < 4; ++ks) O[3] = MFMA32(v0[ks], pw[ks], O[3]);
;     }
; }
	ds_read_b128 v[98:101], v251 offset:0
	ds_read_b128 v[102:105], v252 offset:0
	ds_read_b128 v[106:109], v232 offset:0
	ds_read_b128 v[110:113], v234 offset:0
	ds_read_b128 v[180:183], v251 offset:8192
	ds_read_b128 v[184:187], v252 offset:8192
	ds_read_b128 v[188:191], v232 offset:8192
	ds_read_b128 v[192:195], v234 offset:8192
	s_mov_b32 s1, s0
	v_cvt_f32_u32_e32 v218, s1
	s_nop 0
	v_fma_f32 v0, v179, v218, v244
	s_waitcnt lgkmcnt(8)
	v_mfma_f32_32x32x16_bf16 v[50:65], v[66:69], v[196:199], v[50:65]
	v_fma_f32 v82, 0, v179, v0
	v_add_f32_e32 v83, v179, v0
	v_fma_f32 v84, v178, s8, v0
	v_fma_f32 v85, v179, s9, v0
	v_fma_f32 v86, v178, s28, v0
	v_fma_f32 v87, v179, s29, v0
	v_fma_f32 v88, v178, s30, v0
	v_fma_f32 v89, v179, s31, v0
	v_mfma_f32_32x32x16_bf16 v[50:65], v[70:73], v[200:203], v[50:65]
	v_fma_f32 v90, v178, s34, v0
	v_fma_f32 v91, v179, s35, v0
	v_fma_f32 v92, v178, s10, v0
	v_fma_f32 v93, v179, s11, v0
	v_fma_f32 v94, v178, s20, v0
	v_fma_f32 v95, v179, s21, v0
	v_fma_f32 v96, v178, s2, v0
	v_fma_f32 v97, v179, s3, v0
	v_mfma_f32_32x32x16_bf16 v[50:65], v[74:77], v[204:207], v[50:65]
	v_add_f32_e32 v217, v249, v0
	v_fma_f32 v114, 0, v179, v217
	v_add_f32_e32 v115, v179, v217
	v_fma_f32 v116, v178, s8, v217
	v_fma_f32 v117, v179, s9, v217
	v_fma_f32 v118, v178, s28, v217
	v_fma_f32 v119, v179, s29, v217
	v_fma_f32 v120, v178, s30, v217
	v_mfma_f32_32x32x16_bf16 v[50:65], v[78:81], v[208:211], v[50:65]
	v_fma_f32 v121, v179, s31, v217
	v_fma_f32 v122, v178, s34, v217
	v_fma_f32 v123, v179, s35, v217
	v_fma_f32 v124, v178, s10, v217
	v_fma_f32 v125, v179, s11, v217
	v_fma_f32 v126, v178, s20, v217
	v_fma_f32 v127, v179, s21, v217
	v_fma_f32 v128, v178, s2, v217
	ds_read_b128 v[66:69], v212 offset:53248
	ds_read_b128 v[70:73], v213 offset:53248
	ds_read_b128 v[74:77], v214 offset:53248
	ds_read_b128 v[78:81], v215 offset:53248
	s_waitcnt lgkmcnt(8)
	v_mfma_f32_32x32x16_bf16 v[82:97], v[98:101], v[130:133], v[82:97]
	v_fma_f32 v129, v179, s3, v217
	s_mov_b64 s[12:13], 0x7060000
	v_lshl_add_u64 v[220:221], v[172:173], 0, s[12:13]
	s_add_i32 s4, s5, 0x8000
	s_mov_b32 m0, s4
	s_nop 0
	global_load_lds_dwordx4 v[220:221], off
	v_mfma_f32_32x32x16_bf16 v[82:97], v[102:105], v[134:137], v[82:97]
	s_mov_b64 s[12:13], 0x7068000
	v_lshl_add_u64 v[222:223], v[172:173], 0, s[12:13]
	s_add_i32 s4, s5, 0xa000
	s_mov_b32 m0, s4
	s_nop 0
	global_load_lds_dwordx4 v[222:223], off
	v_mfma_f32_32x32x16_bf16 v[82:97], v[106:109], v[138:141], v[82:97]
	s_mov_b64 s[12:13], 0xa018000
	v_lshl_add_u64 v[220:221], v[170:171], 0, s[12:13]
	s_add_i32 s4, s5, 0x18000
	s_mov_b32 m0, s4
	s_nop 0
	global_load_lds_dwordx4 v[220:221], off
	v_mfma_f32_32x32x16_bf16 v[82:97], v[110:113], v[142:145], v[82:97]
	s_mov_b64 s[12:13], 0xa01a000
	v_lshl_add_u64 v[222:223], v[170:171], 0, s[12:13]
	s_add_i32 s4, s5, 0x1a000
	s_mov_b32 m0, s4
	s_nop 0
	global_load_lds_dwordx4 v[222:223], off
	ds_read_b128 v[98:101], v212 offset:57344
	ds_read_b128 v[102:105], v213 offset:57344
	ds_read_b128 v[106:109], v214 offset:57344
	ds_read_b128 v[110:113], v215 offset:57344
	s_waitcnt lgkmcnt(8)
	v_mfma_f32_32x32x16_bf16 v[114:129], v[180:183], v[130:133], v[114:129]
	v_exp_f32_e32 v82, v82
	v_exp_f32_e32 v83, v83
	v_exp_f32_e32 v84, v84
	v_mfma_f32_32x32x16_bf16 v[114:129], v[184:187], v[134:137], v[114:129]
	v_exp_f32_e32 v85, v85
	v_exp_f32_e32 v86, v86
	v_exp_f32_e32 v87, v87
	v_mfma_f32_32x32x16_bf16 v[114:129], v[188:191], v[138:141], v[114:129]
	v_exp_f32_e32 v88, v88
	v_exp_f32_e32 v89, v89
	v_exp_f32_e32 v90, v90
	v_mfma_f32_32x32x16_bf16 v[114:129], v[192:195], v[142:145], v[114:129]
	v_exp_f32_e32 v91, v91
	v_exp_f32_e32 v92, v92
	v_exp_f32_e32 v93, v93
	ds_read_b128 v[180:183], v212 offset:61440
	ds_read_b128 v[184:187], v213 offset:61440
	ds_read_b128 v[188:191], v214 offset:61440
	ds_read_b128 v[192:195], v215 offset:61440
	s_waitcnt lgkmcnt(8)
; #define LAS __attribute__((address_space(3)))
; #define MFMA32(a, b, c) __builtin_amdgcn_mfma_f32_32x32x16_bf16((a), (b), (c), 0, 0, 0)
; template <bool PV> DI void df_pv_exp(const LAS char* Vst, const DfCtx& c, const bf16x8 (&pw)[4], f32x16 (&O)[4], f32x16& p, f32x16& q, bf16x8 (&pwN)[4], float& l, bool dg, int kv0) {
;     bf16x8 v0[4];
;     if (PV) {
; #pragma unroll
;         for (int ks = 0; ks < 4; ++ks) v0[ks] = ldsv(Vst + c.vad[ks]);
;         MEMFENCE(); }
; #pragma unroll
;     for (int r = 0; r < 16; ++r) p[r] = ex2(p[r]);
;     if (PV) {
;         PIN4(v0);
; #pragma unroll
;         for (int ks = 0; ks < 4; ++ks) O[0] = MFMA32(v0[ks], pw[ks], O[0]);
; #pragma unroll
;         for (int ks = 0; ks < 4; ++ks) v0[ks] = ldsv(Vst + c.vad[ks] + 4096);
;         MEMFENCE(); }
; #pragma unroll
;     for (int r = 0; r < 16; ++r) q[r] = ex2(q[r]);
;     if (PV) {
;         PIN4(v0);
; #pragma unroll
;         for (int ks = 0; ks < 4; ++ks) O[1] = MFMA32(v0[ks], pw[ks], O[1]);
; #pragma unroll
;         for (int ks = 0; ks < 4; ++ks) v0[ks] = ldsv(Vst + c.vad[ks] + 8192);
;         MEMFENCE(); }
;     if (dg) { const int lim = c.tq - kv0 - 4 * c.hi;
; #pragma unroll
;         for (int r = 0; r < 16; ++r) { if ((r & 3) + 8 * (r >> 2) > lim) p[r] = 0.f; if (32 + (r & 3) + 8 * (r >> 2) > lim) q[r] = 0.f; } }
;     float ls = 0.f;
; #pragma unroll
;     for (int r = 0; r < 16; ++r) ls += p[r] + q[r];
;     l += ls;
;     if (PV) {
;         PIN4(v0);
; #pragma unroll
;         for (int ks = 0; ks < 4; ++ks) O[2] = MFMA32(v0[ks], pw[ks], O[2]);
; #pragma unroll
;         for (int ks = 0; ks < 4; ++ks) v0[ks] = ldsv(Vst + c.vad[ks] + 12288);
;         MEMFENCE(); }
;     pwN[0] = pack8<0>(p); pwN[1] = pack8<1>(p); pwN[2] = pack8<0>(q); pwN[3] = pack8<1>(q);
;     if (PV) {
;         PIN4(v0);
; #pragma unroll
;         for (int ks = 0; ks < 4; ++ks) O[3] = MFMA32(v0[ks], pw[ks], O[3]);
;     }
; }
; DI void df_unit(LAS char* lds, int b, int h, int qb, const bf16_t* __restrict__ Q, const bf16_t* __restrict__ K, const bf16_t* __restrict__ VT, const bf16_t* __restrict__ G, bf16_t* __restrict__ MIX,
;                 float lam, float Mb  , const float* __restrict__ subg) {
;     ...
;     int T = T0 + 1;
;     for (; T + 4 <= nt - 2; T += 4) { DF_MAIN(16384, T); DF_MAIN(32768, T + 1); DF_MAIN(49152, T + 2); DF_MAIN(0, T + 3); }
	v_mfma_f32_32x32x16_bf16 v[34:49], v[66:69], v[196:199], v[34:49]
	v_exp_f32_e32 v94, v94
	v_exp_f32_e32 v95, v95
	v_exp_f32_e32 v96, v96
	v_mfma_f32_32x32x16_bf16 v[34:49], v[70:73], v[200:203], v[34:49]
	v_exp_f32_e32 v97, v97
	v_add_f32_e32 v219, v219, v82
	v_add_f32_e32 v219, v219, v83
	v_cvt_pk_bf16_f32 v158, v82, v83
	v_add_f32_e32 v219, v219, v84
	v_mfma_f32_32x32x16_bf16 v[34:49], v[74:77], v[204:207], v[34:49]
	v_add_f32_e32 v219, v219, v85
	v_cvt_pk_bf16_f32 v159, v84, v85
	v_add_f32_e32 v219, v219, v86
	v_add_f32_e32 v219, v219, v87
	v_cvt_pk_bf16_f32 v160, v86, v87
	v_add_f32_e32 v219, v219, v88
	v_mfma_f32_32x32x16_bf16 v[34:49], v[78:81], v[208:211], v[34:49]
	v_add_f32_e32 v219, v219, v89
	v_cvt_pk_bf16_f32 v161, v88, v89
	v_exp_f32_e32 v114, v114
	v_exp_f32_e32 v115, v115
	s_waitcnt lgkmcnt(4)
	v_mfma_f32_32x32x16_bf16 v[18:33], v[98:101], v[196:199], v[18:33]
	v_exp_f32_e32 v116, v116
	v_exp_f32_e32 v117, v117
	v_exp_f32_e32 v118, v118
	v_mfma_f32_32x32x16_bf16 v[18:33], v[102:105], v[200:203], v[18:33]
	v_exp_f32_e32 v119, v119
	v_exp_f32_e32 v120, v120
	v_exp_f32_e32 v121, v121
	v_mfma_f32_32x32x16_bf16 v[18:33], v[106:109], v[204:207], v[18:33]
	v_exp_f32_e32 v122, v122
	v_exp_f32_e32 v123, v123
	v_exp_f32_e32 v124, v124
	v_mfma_f32_32x32x16_bf16 v[18:33], v[110:113], v[208:211], v[18:33]
	v_exp_f32_e32 v125, v125
	v_exp_f32_e32 v126, v126
	v_exp_f32_e32 v127, v127
	s_waitcnt lgkmcnt(0)
	v_mfma_f32_32x32x16_bf16 v[2:17], v[180:183], v[196:199], v[2:17]
	v_exp_f32_e32 v128, v128
	v_exp_f32_e32 v129, v129
	v_add_f32_e32 v219, v219, v90
	v_add_f32_e32 v219, v219, v91
	v_mfma_f32_32x32x16_bf16 v[2:17], v[184:187], v[200:203], v[2:17]
	v_cvt_pk_bf16_f32 v154, v90, v91
	v_add_f32_e32 v219, v219, v92
	v_add_f32_e32 v219, v219, v93
	v_cvt_pk_bf16_f32 v155, v92, v93
	v_add_f32_e32 v219, v219, v94
	v_add_f32_e32 v219, v219, v95
	v_mfma_f32_32x32x16_bf16 v[2:17], v[188:191], v[204:207], v[2:17]
	v_cvt_pk_bf16_f32 v156, v94, v95
	v_add_f32_e32 v219, v219, v96
	v_add_f32_e32 v219, v219, v97
	v_cvt_pk_bf16_f32 v157, v96, v97
	v_add_f32_e32 v216, v216, v114
	v_add_f32_e32 v216, v216, v115
	v_mfma_f32_32x32x16_bf16 v[2:17], v[192:195], v[208:211], v[2:17]
	v_cvt_pk_bf16_f32 v150, v114, v115
	v_add_f32_e32 v216, v216, v116
	v_add_f32_e32 v216, v216, v117
	v_cvt_pk_bf16_f32 v151, v116, v117
	v_add_f32_e32 v216, v216, v118
	v_add_f32_e32 v216, v216, v119
	v_cvt_pk_bf16_f32 v152, v118, v119
	v_add_f32_e32 v216, v216, v120
	v_add_f32_e32 v216, v216, v121
	v_cvt_pk_bf16_f32 v153, v120, v121
	v_add_f32_e32 v216, v216, v122
	v_add_f32_e32 v216, v216, v123
	v_cvt_pk_bf16_f32 v146, v122, v123
	v_add_f32_e32 v216, v216, v124
	v_add_f32_e32 v216, v216, v125
	v_cvt_pk_bf16_f32 v147, v124, v125
	v_add_f32_e32 v216, v216, v126
	v_add_f32_e32 v216, v216, v127
	v_cvt_pk_bf16_f32 v148, v126, v127
	v_add_f32_e32 v216, v216, v128
	v_add_f32_e32 v216, v216, v129
	v_cvt_pk_bf16_f32 v149, v128, v129
	v_add_f32_e32 v194, v219, v216
	v_lshl_add_u64 v[166:167], v[166:167], 0, s[18:19]
	s_mov_b64 s[12:13], 0x40000
	v_lshl_add_u64 v[168:169], v[168:169], 0, s[12:13]
	s_add_i32 s1, s60, 4
	s_addk_i32 s0, 0x100
	s_cmp_le_i32 s1, s15
	s_cbranch_scc1 .LBB0_381
	s_branch .LBB0_385

; #define LAS __attribute__((address_space(3)))
; #define WAIT_BAR0() asm volatile("s_waitcnt vmcnt(0) lgkmcnt(0)\n\ts_barrier" ::: "memory")
; DI void sb_unit(LAS char* lds, int b, int h, int qb, const bf16_t* __restrict__ Q, const bf16_t* __restrict__ K, const bf16_t* __restrict__ VT, const bf16_t* __restrict__ G, bf16_t* __restrict__ MIX) {
;     ...
;         WAIT_BAR0();
;         if (it > 0) { volatile LAS int* fl = flags + ((it & 1) ^ 1) * 8; const int all = fl[0] & fl[1] & fl[2] & fl[3] & fl[4] & fl[5] & fl[6] & fl[7]; if (all) break; }
.LBB0_418:
	s_andn2_b32 s0, 8, s41
	s_lshl_b32 s0, s0, 2
	s_add_i32 s0, s0, 0
	s_add_i32 s0, s0, 0x20000
	s_waitcnt vmcnt(0) lgkmcnt(0)
	s_barrier
	v_mov_b32_e32 v35, s0
	ds_read_b128 v[108:111], v35
	ds_read_b128 v[112:115], v35 offset:16
	s_waitcnt lgkmcnt(0)
	v_and_b32_e32 v37, v109, v108
	v_and_b32_e32 v38, v111, v110
	v_and_b32_e32 v108, v113, v112
	v_and_b32_e32 v109, v115, v114
	v_and_b32_e32 v37, v37, v38
	v_and_b32_e32 v108, v108, v109
	v_and_b32_e32 v35, v37, v108
	v_cmp_ne_u32_e32 vcc, 0, v35
	s_cbranch_vccz .LBB0_420
	s_cbranch_execz .LBB0_418
	s_branch .LBB0_372
